# in-proj epilogue (plain-column variant): the 7 serialized row-scale loads (load, vmcnt(0), use) issued together at the epilogue top into spare registers; on v65
# speedup vs baseline: 1.0072x; 1.0063x over previous
; __device__ __forceinline__ unsigned cvt_pk_bf16(float lo, float hi) { unsigned r; asm volatile("v_cvt_pk_bf16_f32 %0, %1, %2" : "=v"(r) : "v"(lo), "v"(hi)); return r; }
;     __device__ __forceinline__ void operator()(const f32x4 (&acc)[2][2][4][2], const Unit& u, int wr, int wc, int fr, int fq) const {
;     ...
;         const bool act = u.pn >= 6, st = u.pn >= 10;
; #pragma unroll
;         for (int ai = 0; ai < 2; ++ai)
; #pragma unroll
;             for (int m = 0; m < 4; ++m) {
;                 const int row = row0 + ai * HALF + m * 16; const float rs = r1[row];
;                 bf16_t* rowp = O + (size_t)row * PROJ_LD + col0; float s1 = 0.f, s2 = 0.f;
; #pragma unroll
;                 for (int bj = 0; bj < 2; ++bj) {
;                     f32x4 v0 = acc[ai][bj][m][0] * rs, v1 = acc[ai][bj][m][1] * rs;
;                     if (act) {
; #pragma unroll
;                         for (int j = 0; j < 4; ++j) { v0[j] = gelu_tanh(v0[j]); v1[j] = gelu_tanh(v1[j]); }
;                     }
;                     if (st) {
; #pragma unroll
;                         for (int j = 0; j < 4; ++j) { s1 += v0[j] + v1[j]; s2 += v0[j] * v0[j] + v1[j] * v1[j]; }
;                     }
;                     u32x4 w; w.x = cvt_pk_bf16(v0[0], v0[1]); w.y = cvt_pk_bf16(v0[2], v0[3]); w.z = cvt_pk_bf16(v1[0], v1[1]); w.w = cvt_pk_bf16(v1[2], v1[3]);
;                     __builtin_nontemporal_store(w, (u32x4*)(rowp + bj * HALF));
.LBB0_243:
	v_lshl_add_u64 v[128:129], v[178:179], 2, s[46:47]
	global_load_dword v130, v[128:129], off
	global_load_dword v246, v[128:129], off offset:64
	global_load_dword v248, v[128:129], off offset:128
	global_load_dword v250, v[128:129], off offset:192
	global_load_dword v252, v[128:129], off offset:512
	global_load_dword v254, v[128:129], off offset:576
	global_load_dword v152, v[128:129], off offset:640
	s_cmp_lg_u32 s66, 5
	s_cselect_b64 s[8:9], -1, 0
	s_cmp_eq_u32 s66, 5
	s_waitcnt vmcnt(0)
	v_pk_mul_f32 v[136:137], v[126:127], v[130:131] op_sel_hi:[1,0]
	v_pk_mul_f32 v[138:139], v[124:125], v[130:131] op_sel_hi:[1,0]
	v_pk_mul_f32 v[140:141], v[122:123], v[130:131] op_sel_hi:[1,0]
	v_pk_mul_f32 v[142:143], v[120:121], v[130:131] op_sel_hi:[1,0]
	s_cbranch_scc1 .LBB0_245
	v_mul_f32_e32 v132, v142, v142
	v_fma_f32 v132, v132, s85, 1.0
	v_mul_f32_e32 v131, v138, v138
	v_mul_f32_e32 v132, v142, v132
	v_fma_f32 v131, v131, s85, 1.0
	v_mul_f32_e32 v132, 0xc0135761, v132
	v_mul_f32_e32 v131, v138, v131
	v_exp_f32_e32 v133, v132
	v_mul_f32_e32 v132, v139, v139
	v_mul_f32_e32 v131, 0xc0135761, v131
	v_fma_f32 v132, v132, s85, 1.0
	v_exp_f32_e32 v131, v131
	v_mul_f32_e32 v132, v139, v132
	v_mul_f32_e32 v132, 0xc0135761, v132
	v_exp_f32_e32 v135, v132
	v_add_f32_e32 v131, 1.0, v131
	v_rcp_f32_e32 v132, v131
	v_add_f32_e32 v131, 1.0, v133
	v_rcp_f32_e32 v134, v131
	v_add_f32_e32 v131, 1.0, v135
	v_mul_f32_e32 v135, v136, v136
	v_fma_f32 v135, v135, s85, 1.0
	v_mul_f32_e32 v144, v140, v140
	v_mul_f32_e32 v135, v136, v135
	v_fma_f32 v144, v144, s85, 1.0
	v_mul_f32_e32 v135, 0xc0135761, v135
	v_mul_f32_e32 v144, v140, v144
	v_exp_f32_e32 v135, v135
	v_mul_f32_e32 v144, 0xc0135761, v144
	v_exp_f32_e32 v145, v144
	v_rcp_f32_e32 v133, v131
	v_add_f32_e32 v135, 1.0, v135
	v_rcp_f32_e32 v144, v135
	v_add_f32_e32 v135, 1.0, v145
	v_mul_f32_e32 v145, v137, v137
	v_mul_f32_e32 v131, v143, v143
	v_fma_f32 v145, v145, s85, 1.0
	v_mul_f32_e32 v146, v141, v141
	v_fma_f32 v131, v131, s85, 1.0
	v_mul_f32_e32 v145, v137, v145
	v_fma_f32 v146, v146, s85, 1.0
	v_mul_f32_e32 v131, v143, v131
	v_mul_f32_e32 v145, 0xc0135761, v145
	v_mul_f32_e32 v146, v141, v146
	v_mul_f32_e32 v131, 0xc0135761, v131
	v_exp_f32_e32 v145, v145
	v_mul_f32_e32 v146, 0xc0135761, v146
	v_exp_f32_e32 v131, v131
	v_exp_f32_e32 v147, v146
	v_rcp_f32_e32 v146, v135
	v_add_f32_e32 v135, 1.0, v145
	v_add_f32_e32 v131, 1.0, v131
	v_rcp_f32_e32 v145, v135
	v_add_f32_e32 v135, 1.0, v147
	v_rcp_f32_e32 v147, v135
	v_rcp_f32_e32 v135, v131
	v_pk_mul_f32 v[136:137], v[136:137], v[144:145]
	v_pk_mul_f32 v[138:139], v[138:139], v[132:133]
	v_pk_mul_f32 v[140:141], v[140:141], v[146:147]
	v_pk_mul_f32 v[142:143], v[142:143], v[134:135]

;     __device__ __forceinline__ void operator()(const f32x4 (&acc)[2][2][4][2], const Unit& u, int wr, int wc, int fr, int fq) const {
;     ...
;                 const int row = row0 + ai * HALF + m * 16; const float rs = r1[row];
;                 bf16_t* rowp = O + (size_t)row * PROJ_LD + col0; float s1 = 0.f, s2 = 0.f;
; #pragma unroll
;                 for (int bj = 0; bj < 2; ++bj) {
;                     f32x4 v0 = acc[ai][bj][m][0] * rs, v1 = acc[ai][bj][m][1] * rs;
;                     if (act) {
; #pragma unroll
;                         for (int j = 0; j < 4; ++j) { v0[j] = gelu_tanh(v0[j]); v1[j] = gelu_tanh(v1[j]); }
;                     }
.LBB0_260:
	v_or_b32_e32 v130, 16, v178
	s_waitcnt lgkmcnt(1)
	v_ashrrev_i32_e32 v131, 31, v130
	s_waitcnt lgkmcnt(0)
	v_lshl_add_u64 v[132:133], v[130:131], 2, s[46:47]
	v_mov_b32_e32 v132, v246
	s_and_b64 vcc, exec, s[6:7]
	s_nop 0
	v_pk_mul_f32 v[138:139], v[110:111], v[132:133] op_sel_hi:[1,0]
	v_pk_mul_f32 v[142:143], v[108:109], v[132:133] op_sel_hi:[1,0]
	v_pk_mul_f32 v[140:141], v[106:107], v[132:133] op_sel_hi:[1,0]
	v_pk_mul_f32 v[144:145], v[104:105], v[132:133] op_sel_hi:[1,0]
	s_cbranch_vccnz .LBB0_262
	v_mul_f32_e32 v131, v142, v142
	v_fma_f32 v131, v131, s85, 1.0
	v_mul_f32_e32 v133, v144, v144
	v_mul_f32_e32 v131, v142, v131
	v_fma_f32 v133, v133, s85, 1.0
	v_mul_f32_e32 v131, 0xc0135761, v131
	v_mul_f32_e32 v133, v144, v133
	v_exp_f32_e32 v131, v131
	v_mul_f32_e32 v133, 0xc0135761, v133
	v_exp_f32_e32 v133, v133
	v_mul_f32_e32 v134, v143, v143
	v_fma_f32 v134, v134, s85, 1.0
	v_mul_f32_e32 v134, v143, v134
	v_add_f32_e32 v131, 1.0, v131
	v_mul_f32_e32 v134, 0xc0135761, v134
	v_exp_f32_e32 v135, v134
	v_rcp_f32_e32 v134, v131
	v_add_f32_e32 v131, 1.0, v133
	v_mul_f32_e32 v133, v138, v138
	v_fma_f32 v133, v133, s85, 1.0
	v_mul_f32_e32 v137, v140, v140
	v_mul_f32_e32 v133, v138, v133
	v_fma_f32 v137, v137, s85, 1.0
	v_mul_f32_e32 v133, 0xc0135761, v133
	v_mul_f32_e32 v137, v140, v137
	v_exp_f32_e32 v133, v133
	v_mul_f32_e32 v137, 0xc0135761, v137
	v_exp_f32_e32 v137, v137
	v_rcp_f32_e32 v136, v131
	v_add_f32_e32 v133, 1.0, v133
	v_add_f32_e32 v131, 1.0, v135
	v_rcp_f32_e32 v146, v133
	v_add_f32_e32 v133, 1.0, v137
	v_mul_f32_e32 v137, v139, v139
	v_rcp_f32_e32 v135, v131
	v_mul_f32_e32 v131, v145, v145
	v_fma_f32 v137, v137, s85, 1.0
	v_mul_f32_e32 v147, v141, v141
	v_fma_f32 v131, v131, s85, 1.0
	v_mul_f32_e32 v137, v139, v137
	v_fma_f32 v147, v147, s85, 1.0
	v_mul_f32_e32 v131, v145, v131
	v_mul_f32_e32 v137, 0xc0135761, v137
	v_mul_f32_e32 v147, v141, v147
	v_mul_f32_e32 v131, 0xc0135761, v131
	v_exp_f32_e32 v137, v137
	v_mul_f32_e32 v147, 0xc0135761, v147
	v_exp_f32_e32 v131, v131
	v_exp_f32_e32 v149, v147
	v_rcp_f32_e32 v148, v133
	v_add_f32_e32 v133, 1.0, v137
	v_add_f32_e32 v131, 1.0, v131
	v_rcp_f32_e32 v147, v133
	v_add_f32_e32 v133, 1.0, v149
	v_rcp_f32_e32 v149, v133
	v_rcp_f32_e32 v137, v131
	v_pk_mul_f32 v[138:139], v[138:139], v[146:147]
	v_pk_mul_f32 v[142:143], v[142:143], v[134:135]
	v_pk_mul_f32 v[140:141], v[140:141], v[148:149]
	v_pk_mul_f32 v[144:145], v[144:145], v[136:137]

;     __device__ __forceinline__ void operator()(const f32x4 (&acc)[2][2][4][2], const Unit& u, int wr, int wc, int fr, int fq) const {
;     ...
;                 const int row = row0 + ai * HALF + m * 16; const float rs = r1[row];
;                 bf16_t* rowp = O + (size_t)row * PROJ_LD + col0; float s1 = 0.f, s2 = 0.f;
; #pragma unroll
;                 for (int bj = 0; bj < 2; ++bj) {
;                     f32x4 v0 = acc[ai][bj][m][0] * rs, v1 = acc[ai][bj][m][1] * rs;
;                     if (act) {
; #pragma unroll
;                         for (int j = 0; j < 4; ++j) { v0[j] = gelu_tanh(v0[j]); v1[j] = gelu_tanh(v1[j]); }
;                     }
.LBB0_277:
	v_or_b32_e32 v130, 32, v178
	v_ashrrev_i32_e32 v131, 31, v130
	s_waitcnt lgkmcnt(1)
	v_lshl_add_u64 v[132:133], v[130:131], 2, s[46:47]
	v_mov_b32_e32 v132, v248
	s_and_b64 vcc, exec, s[6:7]
	s_nop 0
	v_pk_mul_f32 v[138:139], v[94:95], v[132:133] op_sel_hi:[1,0]
	v_pk_mul_f32 v[142:143], v[92:93], v[132:133] op_sel_hi:[1,0]
	v_pk_mul_f32 v[140:141], v[90:91], v[132:133] op_sel_hi:[1,0]
	v_pk_mul_f32 v[144:145], v[88:89], v[132:133] op_sel_hi:[1,0]
	s_cbranch_vccnz .LBB0_279
	v_mul_f32_e32 v131, v142, v142
	v_fma_f32 v131, v131, s85, 1.0
	v_mul_f32_e32 v133, v144, v144
	v_mul_f32_e32 v131, v142, v131
	v_fma_f32 v133, v133, s85, 1.0
	v_mul_f32_e32 v131, 0xc0135761, v131
	v_mul_f32_e32 v133, v144, v133
	v_exp_f32_e32 v131, v131
	v_mul_f32_e32 v133, 0xc0135761, v133
	v_exp_f32_e32 v133, v133
	s_waitcnt lgkmcnt(0)
	v_mul_f32_e32 v134, v143, v143
	v_fma_f32 v134, v134, s85, 1.0
	v_mul_f32_e32 v134, v143, v134
	v_add_f32_e32 v131, 1.0, v131
	v_mul_f32_e32 v134, 0xc0135761, v134
	v_exp_f32_e32 v135, v134
	v_rcp_f32_e32 v134, v131
	v_add_f32_e32 v131, 1.0, v133
	v_mul_f32_e32 v133, v138, v138
	v_fma_f32 v133, v133, s85, 1.0
	v_mul_f32_e32 v137, v140, v140
	v_mul_f32_e32 v133, v138, v133
	v_fma_f32 v137, v137, s85, 1.0
	v_mul_f32_e32 v133, 0xc0135761, v133
	v_mul_f32_e32 v137, v140, v137
	v_exp_f32_e32 v133, v133
	v_mul_f32_e32 v137, 0xc0135761, v137
	v_exp_f32_e32 v137, v137
	v_rcp_f32_e32 v136, v131
	v_add_f32_e32 v133, 1.0, v133
	v_add_f32_e32 v131, 1.0, v135
	v_rcp_f32_e32 v146, v133
	v_add_f32_e32 v133, 1.0, v137
	v_mul_f32_e32 v137, v139, v139
	v_rcp_f32_e32 v135, v131
	v_mul_f32_e32 v131, v145, v145
	v_fma_f32 v137, v137, s85, 1.0
	v_mul_f32_e32 v147, v141, v141
	v_fma_f32 v131, v131, s85, 1.0
	v_mul_f32_e32 v137, v139, v137
	v_fma_f32 v147, v147, s85, 1.0
	v_mul_f32_e32 v131, v145, v131
	v_mul_f32_e32 v137, 0xc0135761, v137
	v_mul_f32_e32 v147, v141, v147
	v_mul_f32_e32 v131, 0xc0135761, v131
	v_exp_f32_e32 v137, v137
	v_mul_f32_e32 v147, 0xc0135761, v147
	v_exp_f32_e32 v131, v131
	v_exp_f32_e32 v149, v147
	v_rcp_f32_e32 v148, v133
	v_add_f32_e32 v133, 1.0, v137
	v_add_f32_e32 v131, 1.0, v131
	v_rcp_f32_e32 v147, v133
	v_add_f32_e32 v133, 1.0, v149
	v_rcp_f32_e32 v149, v133
	v_rcp_f32_e32 v137, v131
	v_pk_mul_f32 v[138:139], v[138:139], v[146:147]
	v_pk_mul_f32 v[142:143], v[142:143], v[134:135]
	v_pk_mul_f32 v[140:141], v[140:141], v[148:149]
	v_pk_mul_f32 v[144:145], v[144:145], v[136:137]

;     __device__ __forceinline__ void operator()(const f32x4 (&acc)[2][2][4][2], const Unit& u, int wr, int wc, int fr, int fq) const {
;     ...
;                 const int row = row0 + ai * HALF + m * 16; const float rs = r1[row];
;                 bf16_t* rowp = O + (size_t)row * PROJ_LD + col0; float s1 = 0.f, s2 = 0.f;
; #pragma unroll
;                 for (int bj = 0; bj < 2; ++bj) {
;                     f32x4 v0 = acc[ai][bj][m][0] * rs, v1 = acc[ai][bj][m][1] * rs;
;                     if (act) {
; #pragma unroll
;                         for (int j = 0; j < 4; ++j) { v0[j] = gelu_tanh(v0[j]); v1[j] = gelu_tanh(v1[j]); }
;                     }
.LBB0_294:
	v_or_b32_e32 v130, 48, v178
	v_ashrrev_i32_e32 v131, 31, v130
	s_waitcnt lgkmcnt(1)
	v_lshl_add_u64 v[132:133], v[130:131], 2, s[46:47]
	v_mov_b32_e32 v132, v250
	s_and_b64 vcc, exec, s[6:7]
	s_nop 0
	v_pk_mul_f32 v[138:139], v[78:79], v[132:133] op_sel_hi:[1,0]
	v_pk_mul_f32 v[142:143], v[76:77], v[132:133] op_sel_hi:[1,0]
	v_pk_mul_f32 v[140:141], v[74:75], v[132:133] op_sel_hi:[1,0]
	v_pk_mul_f32 v[144:145], v[72:73], v[132:133] op_sel_hi:[1,0]
	s_cbranch_vccnz .LBB0_296
	v_mul_f32_e32 v131, v142, v142
	v_fma_f32 v131, v131, s85, 1.0
	v_mul_f32_e32 v133, v144, v144
	v_mul_f32_e32 v131, v142, v131
	v_fma_f32 v133, v133, s85, 1.0
	v_mul_f32_e32 v131, 0xc0135761, v131
	v_mul_f32_e32 v133, v144, v133
	v_exp_f32_e32 v131, v131
	v_mul_f32_e32 v133, 0xc0135761, v133
	v_exp_f32_e32 v133, v133
	s_waitcnt lgkmcnt(0)
	v_mul_f32_e32 v134, v143, v143
	v_fma_f32 v134, v134, s85, 1.0
	v_mul_f32_e32 v134, v143, v134
	v_add_f32_e32 v131, 1.0, v131
	v_mul_f32_e32 v134, 0xc0135761, v134
	v_exp_f32_e32 v135, v134
	v_rcp_f32_e32 v134, v131
	v_add_f32_e32 v131, 1.0, v133
	v_mul_f32_e32 v133, v138, v138
	v_fma_f32 v133, v133, s85, 1.0
	v_mul_f32_e32 v137, v140, v140
	v_mul_f32_e32 v133, v138, v133
	v_fma_f32 v137, v137, s85, 1.0
	v_mul_f32_e32 v133, 0xc0135761, v133
	v_mul_f32_e32 v137, v140, v137
	v_exp_f32_e32 v133, v133
	v_mul_f32_e32 v137, 0xc0135761, v137
	v_exp_f32_e32 v137, v137
	v_rcp_f32_e32 v136, v131
	v_add_f32_e32 v133, 1.0, v133
	v_add_f32_e32 v131, 1.0, v135
	v_rcp_f32_e32 v146, v133
	v_add_f32_e32 v133, 1.0, v137
	v_mul_f32_e32 v137, v139, v139
	v_rcp_f32_e32 v135, v131
	v_mul_f32_e32 v131, v145, v145
	v_fma_f32 v137, v137, s85, 1.0
	v_mul_f32_e32 v147, v141, v141
	v_fma_f32 v131, v131, s85, 1.0
	v_mul_f32_e32 v137, v139, v137
	v_fma_f32 v147, v147, s85, 1.0
	v_mul_f32_e32 v131, v145, v131
	v_mul_f32_e32 v137, 0xc0135761, v137
	v_mul_f32_e32 v147, v141, v147
	v_mul_f32_e32 v131, 0xc0135761, v131
	v_exp_f32_e32 v137, v137
	v_mul_f32_e32 v147, 0xc0135761, v147
	v_exp_f32_e32 v131, v131
	v_exp_f32_e32 v149, v147
	v_rcp_f32_e32 v148, v133
	v_add_f32_e32 v133, 1.0, v137
	v_add_f32_e32 v131, 1.0, v131
	v_rcp_f32_e32 v147, v133
	v_add_f32_e32 v133, 1.0, v149
	v_rcp_f32_e32 v149, v133
	v_rcp_f32_e32 v137, v131
	v_pk_mul_f32 v[138:139], v[138:139], v[146:147]
	v_pk_mul_f32 v[142:143], v[142:143], v[134:135]
	v_pk_mul_f32 v[140:141], v[140:141], v[148:149]
	v_pk_mul_f32 v[144:145], v[144:145], v[136:137]

;     __device__ __forceinline__ void operator()(const f32x4 (&acc)[2][2][4][2], const Unit& u, int wr, int wc, int fr, int fq) const {
;     ...
;                 const int row = row0 + ai * HALF + m * 16; const float rs = r1[row];
;                 bf16_t* rowp = O + (size_t)row * PROJ_LD + col0; float s1 = 0.f, s2 = 0.f;
; #pragma unroll
;                 for (int bj = 0; bj < 2; ++bj) {
;                     f32x4 v0 = acc[ai][bj][m][0] * rs, v1 = acc[ai][bj][m][1] * rs;
;                     if (act) {
; #pragma unroll
;                         for (int j = 0; j < 4; ++j) { v0[j] = gelu_tanh(v0[j]); v1[j] = gelu_tanh(v1[j]); }
;                     }
.LBB0_311:
	v_mov_b32_e32 v130, v252
	s_and_b64 vcc, exec, s[6:7]
	s_nop 0
	v_pk_mul_f32 v[136:137], v[62:63], v[130:131] op_sel_hi:[1,0]
	v_pk_mul_f32 v[140:141], v[60:61], v[130:131] op_sel_hi:[1,0]
	v_pk_mul_f32 v[138:139], v[58:59], v[130:131] op_sel_hi:[1,0]
	v_pk_mul_f32 v[142:143], v[56:57], v[130:131] op_sel_hi:[1,0]
	s_cbranch_vccnz .LBB0_313
	s_waitcnt lgkmcnt(1)
	v_mul_f32_e32 v132, v142, v142
	v_fma_f32 v132, v132, s85, 1.0
	v_mul_f32_e32 v131, v140, v140
	v_mul_f32_e32 v132, v142, v132
	v_fma_f32 v131, v131, s85, 1.0
	v_mul_f32_e32 v132, 0xc0135761, v132
	v_mul_f32_e32 v131, v140, v131
	v_exp_f32_e32 v133, v132
	v_mul_f32_e32 v132, v141, v141
	v_mul_f32_e32 v131, 0xc0135761, v131
	v_fma_f32 v132, v132, s85, 1.0
	v_exp_f32_e32 v131, v131
	v_mul_f32_e32 v132, v141, v132
	v_mul_f32_e32 v132, 0xc0135761, v132
	v_exp_f32_e32 v135, v132
	v_add_f32_e32 v131, 1.0, v131
	v_rcp_f32_e32 v132, v131
	v_add_f32_e32 v131, 1.0, v133
	s_waitcnt lgkmcnt(0)
	v_rcp_f32_e32 v134, v131
	v_add_f32_e32 v131, 1.0, v135
	v_mul_f32_e32 v135, v136, v136
	v_fma_f32 v135, v135, s85, 1.0
	v_mul_f32_e32 v144, v138, v138
	v_mul_f32_e32 v135, v136, v135
	v_fma_f32 v144, v144, s85, 1.0
	v_mul_f32_e32 v135, 0xc0135761, v135
	v_mul_f32_e32 v144, v138, v144
	v_exp_f32_e32 v135, v135
	v_mul_f32_e32 v144, 0xc0135761, v144
	v_exp_f32_e32 v145, v144
	v_rcp_f32_e32 v133, v131
	v_add_f32_e32 v135, 1.0, v135
	v_rcp_f32_e32 v144, v135
	v_add_f32_e32 v135, 1.0, v145
	v_mul_f32_e32 v145, v137, v137
	v_mul_f32_e32 v131, v143, v143
	v_fma_f32 v145, v145, s85, 1.0
	v_mul_f32_e32 v146, v139, v139
	v_fma_f32 v131, v131, s85, 1.0
	v_mul_f32_e32 v145, v137, v145
	v_fma_f32 v146, v146, s85, 1.0
	v_mul_f32_e32 v131, v143, v131
	v_mul_f32_e32 v145, 0xc0135761, v145
	v_mul_f32_e32 v146, v139, v146
	v_mul_f32_e32 v131, 0xc0135761, v131
	v_exp_f32_e32 v145, v145
	v_mul_f32_e32 v146, 0xc0135761, v146
	v_exp_f32_e32 v131, v131
	v_exp_f32_e32 v147, v146
	v_rcp_f32_e32 v146, v135
	v_add_f32_e32 v135, 1.0, v145
	v_add_f32_e32 v131, 1.0, v131
	v_rcp_f32_e32 v145, v135
	v_add_f32_e32 v135, 1.0, v147
	v_rcp_f32_e32 v147, v135
	v_rcp_f32_e32 v135, v131
	v_pk_mul_f32 v[136:137], v[136:137], v[144:145]
	v_pk_mul_f32 v[140:141], v[140:141], v[132:133]
	v_pk_mul_f32 v[138:139], v[138:139], v[146:147]
	v_pk_mul_f32 v[142:143], v[142:143], v[134:135]

;     __device__ __forceinline__ void operator()(const f32x4 (&acc)[2][2][4][2], const Unit& u, int wr, int wc, int fr, int fq) const {
;     ...
;                 const int row = row0 + ai * HALF + m * 16; const float rs = r1[row];
;                 bf16_t* rowp = O + (size_t)row * PROJ_LD + col0; float s1 = 0.f, s2 = 0.f;
; #pragma unroll
;                 for (int bj = 0; bj < 2; ++bj) {
;                     f32x4 v0 = acc[ai][bj][m][0] * rs, v1 = acc[ai][bj][m][1] * rs;
;                     if (act) {
; #pragma unroll
;                         for (int j = 0; j < 4; ++j) { v0[j] = gelu_tanh(v0[j]); v1[j] = gelu_tanh(v1[j]); }
;                     }
.LBB0_328:
	v_mov_b32_e32 v130, v254
	s_and_b64 vcc, exec, s[6:7]
	s_waitcnt lgkmcnt(1)
	v_pk_mul_f32 v[136:137], v[46:47], v[130:131] op_sel_hi:[1,0]
	v_pk_mul_f32 v[140:141], v[44:45], v[130:131] op_sel_hi:[1,0]
	v_pk_mul_f32 v[138:139], v[42:43], v[130:131] op_sel_hi:[1,0]
	v_pk_mul_f32 v[142:143], v[40:41], v[130:131] op_sel_hi:[1,0]
	s_cbranch_vccnz .LBB0_330
	v_mul_f32_e32 v132, v142, v142
	v_fma_f32 v132, v132, s85, 1.0
	v_mul_f32_e32 v131, v140, v140
	v_mul_f32_e32 v132, v142, v132
	v_fma_f32 v131, v131, s85, 1.0
	v_mul_f32_e32 v132, 0xc0135761, v132
	v_mul_f32_e32 v131, v140, v131
	s_waitcnt lgkmcnt(0)
	v_exp_f32_e32 v133, v132
	v_mul_f32_e32 v132, v141, v141
	v_mul_f32_e32 v131, 0xc0135761, v131
	v_fma_f32 v132, v132, s85, 1.0
	v_exp_f32_e32 v131, v131
	v_mul_f32_e32 v132, v141, v132
	v_mul_f32_e32 v132, 0xc0135761, v132
	v_exp_f32_e32 v135, v132
	v_add_f32_e32 v131, 1.0, v131
	v_rcp_f32_e32 v132, v131
	v_add_f32_e32 v131, 1.0, v133
	v_rcp_f32_e32 v134, v131
	v_add_f32_e32 v131, 1.0, v135
	v_mul_f32_e32 v135, v136, v136
	v_fma_f32 v135, v135, s85, 1.0
	v_mul_f32_e32 v144, v138, v138
	v_mul_f32_e32 v135, v136, v135
	v_fma_f32 v144, v144, s85, 1.0
	v_mul_f32_e32 v135, 0xc0135761, v135
	v_mul_f32_e32 v144, v138, v144
	v_exp_f32_e32 v135, v135
	v_mul_f32_e32 v144, 0xc0135761, v144
	v_exp_f32_e32 v145, v144
	v_rcp_f32_e32 v133, v131
	v_add_f32_e32 v135, 1.0, v135
	v_rcp_f32_e32 v144, v135
	v_add_f32_e32 v135, 1.0, v145
	v_mul_f32_e32 v145, v137, v137
	v_mul_f32_e32 v131, v143, v143
	v_fma_f32 v145, v145, s85, 1.0
	v_mul_f32_e32 v146, v139, v139
	v_fma_f32 v131, v131, s85, 1.0
	v_mul_f32_e32 v145, v137, v145
	v_fma_f32 v146, v146, s85, 1.0
	v_mul_f32_e32 v131, v143, v131
	v_mul_f32_e32 v145, 0xc0135761, v145
	v_mul_f32_e32 v146, v139, v146
	v_mul_f32_e32 v131, 0xc0135761, v131
	v_exp_f32_e32 v145, v145
	v_mul_f32_e32 v146, 0xc0135761, v146
	v_exp_f32_e32 v131, v131
	v_exp_f32_e32 v147, v146
	v_rcp_f32_e32 v146, v135
	v_add_f32_e32 v135, 1.0, v145
	v_add_f32_e32 v131, 1.0, v131
	v_rcp_f32_e32 v145, v135
	v_add_f32_e32 v135, 1.0, v147
	v_rcp_f32_e32 v147, v135
	v_rcp_f32_e32 v135, v131
	v_pk_mul_f32 v[136:137], v[136:137], v[144:145]
	v_pk_mul_f32 v[140:141], v[140:141], v[132:133]
	v_pk_mul_f32 v[138:139], v[138:139], v[146:147]
	v_pk_mul_f32 v[142:143], v[142:143], v[134:135]

;     __device__ __forceinline__ void operator()(const f32x4 (&acc)[2][2][4][2], const Unit& u, int wr, int wc, int fr, int fq) const {
;     ...
;                 const int row = row0 + ai * HALF + m * 16; const float rs = r1[row];
;                 bf16_t* rowp = O + (size_t)row * PROJ_LD + col0; float s1 = 0.f, s2 = 0.f;
; #pragma unroll
;                 for (int bj = 0; bj < 2; ++bj) {
;                     f32x4 v0 = acc[ai][bj][m][0] * rs, v1 = acc[ai][bj][m][1] * rs;
;                     if (act) {
; #pragma unroll
;                         for (int j = 0; j < 4; ++j) { v0[j] = gelu_tanh(v0[j]); v1[j] = gelu_tanh(v1[j]); }
;                     }
.LBB0_345:
	v_mov_b32_e32 v130, v152
	s_and_b64 vcc, exec, s[6:7]
	s_waitcnt lgkmcnt(1)
	v_pk_mul_f32 v[136:137], v[30:31], v[130:131] op_sel_hi:[1,0]
	v_pk_mul_f32 v[140:141], v[28:29], v[130:131] op_sel_hi:[1,0]
	v_pk_mul_f32 v[138:139], v[26:27], v[130:131] op_sel_hi:[1,0]
	v_pk_mul_f32 v[142:143], v[24:25], v[130:131] op_sel_hi:[1,0]
	s_cbranch_vccnz .LBB0_347
	v_mul_f32_e32 v132, v142, v142
	v_fma_f32 v132, v132, s85, 1.0
	v_mul_f32_e32 v131, v140, v140
	v_mul_f32_e32 v132, v142, v132
	v_fma_f32 v131, v131, s85, 1.0
	v_mul_f32_e32 v132, 0xc0135761, v132
	v_mul_f32_e32 v131, v140, v131
	s_waitcnt lgkmcnt(0)
	v_exp_f32_e32 v133, v132
	v_mul_f32_e32 v132, v141, v141
	v_mul_f32_e32 v131, 0xc0135761, v131
	v_fma_f32 v132, v132, s85, 1.0
	v_exp_f32_e32 v131, v131
	v_mul_f32_e32 v132, v141, v132
	v_mul_f32_e32 v132, 0xc0135761, v132
	v_exp_f32_e32 v135, v132
	v_add_f32_e32 v131, 1.0, v131
	v_rcp_f32_e32 v132, v131
	v_add_f32_e32 v131, 1.0, v133
	v_rcp_f32_e32 v134, v131
	v_add_f32_e32 v131, 1.0, v135
	v_mul_f32_e32 v135, v136, v136
	v_fma_f32 v135, v135, s85, 1.0
	v_mul_f32_e32 v144, v138, v138
	v_mul_f32_e32 v135, v136, v135
	v_fma_f32 v144, v144, s85, 1.0
	v_mul_f32_e32 v135, 0xc0135761, v135
	v_mul_f32_e32 v144, v138, v144
	v_exp_f32_e32 v135, v135
	v_mul_f32_e32 v144, 0xc0135761, v144
	v_exp_f32_e32 v145, v144
	v_rcp_f32_e32 v133, v131
	v_add_f32_e32 v135, 1.0, v135
	v_rcp_f32_e32 v144, v135
	v_add_f32_e32 v135, 1.0, v145
	v_mul_f32_e32 v145, v137, v137
	v_mul_f32_e32 v131, v143, v143
	v_fma_f32 v145, v145, s85, 1.0
	v_mul_f32_e32 v146, v139, v139
	v_fma_f32 v131, v131, s85, 1.0
	v_mul_f32_e32 v145, v137, v145
	v_fma_f32 v146, v146, s85, 1.0
	v_mul_f32_e32 v131, v143, v131
	v_mul_f32_e32 v145, 0xc0135761, v145
	v_mul_f32_e32 v146, v139, v146
	v_mul_f32_e32 v131, 0xc0135761, v131
	v_exp_f32_e32 v145, v145
	v_mul_f32_e32 v146, 0xc0135761, v146
	v_exp_f32_e32 v131, v131
	v_exp_f32_e32 v147, v146
	v_rcp_f32_e32 v146, v135
	v_add_f32_e32 v135, 1.0, v145
	v_add_f32_e32 v131, 1.0, v131
	v_rcp_f32_e32 v145, v135
	v_add_f32_e32 v135, 1.0, v147
	v_rcp_f32_e32 v147, v135
	v_rcp_f32_e32 v135, v131
	v_pk_mul_f32 v[136:137], v[136:137], v[144:145]
	v_pk_mul_f32 v[140:141], v[140:141], v[132:133]
	v_pk_mul_f32 v[138:139], v[138:139], v[146:147]
	v_pk_mul_f32 v[142:143], v[142:143], v[134:135]
